# software-pipelined k-loops for gate/up and down/out GEMMs (LDS fragment prefetch, DMA issued right after barrier)
# speedup vs baseline: 1.0465x; 1.0465x over previous
.LBB0_83:
	s_ashr_i32 s14, s18, 31
	v_mov_b32_e32 v129, v127
	s_lshr_b32 s14, s14, 27
	s_add_i32 s14, s18, s14
	s_waitcnt vmcnt(6)
	v_ashrrev_i32_e32 v20, 6, v129
	s_waitcnt vmcnt(5)
	v_bfe_u32 v24, v129, 3, 3
	v_lshlrev_b32_e32 v25, 3, v20
	s_ashr_i32 s20, s14, 5
	s_and_b32 s14, s14, 0x3ffffe0
	v_or_b32_e32 v12, v25, v24
	s_sub_i32 s19, s18, s14
	v_lshrrev_b32_e32 v26, 1, v12
	s_mulk_i32 s19, 0xc0
	v_lshrrev_b32_e32 v0, 31, v129
	v_xor_b32_e32 v2, v26, v129
	v_add_u32_e32 v21, v20, v0
	v_and_b32_e32 v23, 63, v129
	v_add_u32_e32 v0, s19, v12
	v_lshlrev_b32_e32 v2, 4, v2
	v_add_u32_e32 v14, 32, v12
	v_ashrrev_i32_e32 v1, 31, v0
	v_and_b32_e32 v124, 0x70, v2
	v_add_u32_e32 v2, s19, v14
	v_add_u32_e32 v16, 64, v12
	s_add_i32 s15, s19, 0x80
	v_lshlrev_b32_e32 v23, 4, v23
	v_lshlrev_b64 v[0:1], 11, v[0:1]
	v_ashrrev_i32_e32 v3, 31, v2
	v_add_u32_e32 v4, s19, v16
	v_add_u32_e32 v18, 0x60, v12
	v_add_u32_e32 v8, s15, v12
	s_add_i32 s15, s19, 0xa0
	v_lshl_or_b32 v142, v20, 10, v23
	v_lshl_add_u64 v[0:1], s[6:7], 0, v[0:1]
	v_lshlrev_b64 v[2:3], 11, v[2:3]
	v_ashrrev_i32_e32 v5, 31, v4
	v_add_u32_e32 v6, s19, v18
	v_add_u32_e32 v10, s15, v12
	v_readfirstlane_b32 s15, v142
	v_add_u32_e32 v144, 0x1000, v142
	v_lshl_add_u64 v[0:1], v[0:1], 0, v[124:125]
	v_lshl_add_u64 v[2:3], s[6:7], 0, v[2:3]
	v_lshlrev_b64 v[4:5], 11, v[4:5]
	v_ashrrev_i32_e32 v7, 31, v6
	s_mov_b32 m0, s15
	v_readfirstlane_b32 s15, v144
	v_add_u32_e32 v145, 0x2000, v142
	s_lshl_b32 s14, s20, 7
	v_lshl_add_u64 v[2:3], v[2:3], 0, v[124:125]
	v_lshl_add_u64 v[4:5], s[6:7], 0, v[4:5]
	v_lshlrev_b64 v[6:7], 11, v[6:7]
	v_ashrrev_i32_e32 v9, 31, v8
	global_load_lds_dwordx4 v[0:1], off
	s_mov_b32 m0, s15
	v_readfirstlane_b32 s15, v145
	v_add_u32_e32 v146, 0x3000, v142
	v_lshl_add_u64 v[4:5], v[4:5], 0, v[124:125]
	v_lshl_add_u64 v[6:7], s[6:7], 0, v[6:7]
	v_lshlrev_b64 v[8:9], 11, v[8:9]
	v_ashrrev_i32_e32 v11, 31, v10
	v_add_u32_e32 v12, s14, v12
	global_load_lds_dwordx4 v[2:3], off
	s_mov_b32 m0, s15
	v_readfirstlane_b32 s15, v146
	v_add_u32_e32 v147, 0x4000, v142
	v_lshl_add_u64 v[6:7], v[6:7], 0, v[124:125]
	v_lshl_add_u64 v[8:9], s[6:7], 0, v[8:9]
	v_lshlrev_b64 v[10:11], 11, v[10:11]
	v_ashrrev_i32_e32 v13, 31, v12
	v_add_u32_e32 v14, s14, v14
	global_load_lds_dwordx4 v[4:5], off
	s_mov_b32 m0, s15
	v_readfirstlane_b32 s15, v147
	v_add_u32_e32 v148, 0x5000, v142
	v_lshl_add_u64 v[8:9], v[8:9], 0, v[124:125]
	v_lshl_add_u64 v[10:11], s[6:7], 0, v[10:11]
	v_lshlrev_b64 v[12:13], 11, v[12:13]
	v_ashrrev_i32_e32 v15, 31, v14
	v_add_u32_e32 v16, s14, v16
	v_add_u32_e32 v143, 0xc000, v142
	global_load_lds_dwordx4 v[6:7], off
	s_mov_b32 m0, s15
	v_readfirstlane_b32 s15, v148
	v_lshl_add_u64 v[10:11], v[10:11], 0, v[124:125]
	v_lshl_add_u64 v[12:13], s[12:13], 0, v[12:13]
	v_lshlrev_b64 v[14:15], 11, v[14:15]
	v_ashrrev_i32_e32 v17, 31, v16
	v_add_u32_e32 v18, s14, v18
	global_load_lds_dwordx4 v[8:9], off
	s_mov_b32 m0, s15
	v_readfirstlane_b32 s15, v143
	v_add_u32_e32 v150, 0xd000, v142
	v_lshl_add_u64 v[12:13], v[12:13], 0, v[124:125]
	v_lshl_add_u64 v[14:15], s[12:13], 0, v[14:15]
	v_lshlrev_b64 v[16:17], 11, v[16:17]
	v_ashrrev_i32_e32 v19, 31, v18
	global_load_lds_dwordx4 v[10:11], off
	s_mov_b32 m0, s15
	v_readfirstlane_b32 s15, v150
	v_add_u32_e32 v153, 0xe000, v142
	v_lshl_add_u64 v[14:15], v[14:15], 0, v[124:125]
	v_lshl_add_u64 v[16:17], s[12:13], 0, v[16:17]
	v_lshlrev_b64 v[18:19], 11, v[18:19]
	global_load_lds_dwordx4 v[12:13], off
	s_mov_b32 m0, s15
	v_readfirstlane_b32 s15, v153
	v_add_u32_e32 v154, 0xf000, v142
	v_lshl_add_u64 v[16:17], v[16:17], 0, v[124:125]
	v_lshl_add_u64 v[18:19], s[12:13], 0, v[18:19]
	global_load_lds_dwordx4 v[14:15], off
	s_mov_b32 m0, s15
	v_readfirstlane_b32 s15, v154
	v_lshl_add_u64 v[18:19], v[18:19], 0, v[124:125]
	global_load_lds_dwordx4 v[16:17], off
	s_mov_b32 m0, s15
	v_lshrrev_b32_e32 v22, 1, v21
	global_load_lds_dwordx4 v[18:19], off
	v_and_b32_e32 v149, 31, v129
	v_mul_lo_u32 v152, v22, s80
	v_and_b32_e32 v0, -2, v21
	v_or_b32_e32 v1, v152, v149
	v_sub_u32_e32 v151, v20, v0
	v_lshlrev_b32_e32 v155, 7, v1
	v_lshlrev_b32_e32 v1, 7, v149
	v_lshrrev_b32_e32 v23, 1, v129
	v_lshl_or_b32 v182, v151, 13, v1
	v_bfe_u32 v1, v129, 5, 1
	v_bfe_u32 v0, v129, 1, 3
	v_bitop3_b32 v2, v1, v23, 7 bitop3:0x78
	v_lshlrev_b32_e32 v184, 4, v2
	v_bitop3_b32 v2, v1, v0, 2 bitop3:0x36
	v_lshlrev_b32_e32 v185, 4, v2
	v_bitop3_b32 v2, v1, v0, 4 bitop3:0x36
	v_bitop3_b32 v0, v1, v0, 6 bitop3:0x36
	v_lshlrev_b32_e32 v187, 4, v0
	v_bitop3_b32 v0, v26, 7, v129 bitop3:0x48
	s_mul_i32 s15, s18, 0xc0
	v_lshlrev_b32_e32 v124, 4, v0
	v_or_b32_e32 v0, s15, v24
	v_add_u32_e32 v0, v0, v25
	s_mul_i32 s21, s20, 0x1800
	v_subrev_u32_e32 v0, s21, v0
	v_ashrrev_i32_e32 v1, 31, v0
	v_or_b32_e32 v4, 32, v24
	v_lshlrev_b32_e32 v186, 4, v2
	v_lshlrev_b64 v[2:3], 11, v[0:1]
	v_or_b32_e32 v1, s15, v4
	v_add_u32_e32 v1, v1, v25
	v_lshl_add_u64 v[96:97], s[6:7], 0, v[2:3]
	v_subrev_u32_e32 v2, s21, v1
	v_ashrrev_i32_e32 v3, 31, v2
	v_or_b32_e32 v5, 64, v24
	v_lshlrev_b64 v[2:3], 11, v[2:3]
	v_add3_u32 v1, v5, s15, v25
	v_lshl_add_u64 v[98:99], s[6:7], 0, v[2:3]
	v_subrev_u32_e32 v2, s21, v1
	v_ashrrev_i32_e32 v3, 31, v2
	v_or_b32_e32 v6, 0x60, v24
	v_lshlrev_b64 v[2:3], 11, v[2:3]
	v_add3_u32 v1, v6, s15, v25
	v_lshl_add_u64 v[100:101], s[6:7], 0, v[2:3]
	v_subrev_u32_e32 v2, s21, v1
	v_ashrrev_i32_e32 v3, 31, v2
	v_lshlrev_b64 v[2:3], 11, v[2:3]
	v_lshl_add_u64 v[102:103], s[6:7], 0, v[2:3]
	v_add_u32_e32 v2, 0x80, v0
	v_add_u32_e32 v0, 0xa0, v0
	v_ashrrev_i32_e32 v1, 31, v0
	v_lshlrev_b64 v[0:1], 11, v[0:1]
	v_lshl_add_u64 v[106:107], s[6:7], 0, v[0:1]
	v_or_b32_e32 v0, s14, v24
	v_add_u32_e32 v0, v0, v25
	v_ashrrev_i32_e32 v1, 31, v0
	v_lshlrev_b64 v[0:1], 11, v[0:1]
	v_lshl_add_u64 v[108:109], s[10:11], 0, v[0:1]
	v_or_b32_e32 v0, s14, v4
	v_add_u32_e32 v0, v0, v25
	v_ashrrev_i32_e32 v1, 31, v0
	v_lshlrev_b64 v[0:1], 11, v[0:1]
	v_lshl_add_u64 v[110:111], s[10:11], 0, v[0:1]
	v_or_b32_e32 v0, s14, v5
	v_add_u32_e32 v0, v0, v25
	v_ashrrev_i32_e32 v1, 31, v0
	v_lshlrev_b64 v[0:1], 11, v[0:1]
	v_lshl_add_u64 v[112:113], s[10:11], 0, v[0:1]
	v_or_b32_e32 v0, s14, v6
	v_add_u32_e32 v0, v0, v25
	s_waitcnt vmcnt(0)
	v_ashrrev_i32_e32 v3, 31, v2
	v_ashrrev_i32_e32 v1, 31, v0
	v_lshlrev_b64 v[2:3], 11, v[2:3]
	v_lshlrev_b64 v[0:1], 11, v[0:1]
	v_mov_b32_e32 v64, 0
	v_add_u32_e32 v183, 0x10000, v182
	v_lshl_add_u64 v[104:105], s[6:7], 0, v[2:3]
	v_lshl_add_u64 v[114:115], s[10:11], 0, v[0:1]
	s_mov_b32 s21, 0
	v_mov_b32_e32 v65, v64
	v_mov_b32_e32 v66, v64
	v_mov_b32_e32 v67, v64
	v_mov_b32_e32 v68, v64
	v_mov_b32_e32 v69, v64
	v_mov_b32_e32 v70, v64
	v_mov_b32_e32 v71, v64
	v_mov_b32_e32 v72, v64
	v_mov_b32_e32 v73, v64
	v_mov_b32_e32 v74, v64
	v_mov_b32_e32 v75, v64
	v_mov_b32_e32 v76, v64
	v_mov_b32_e32 v77, v64
	v_mov_b32_e32 v78, v64
	v_mov_b32_e32 v79, v64
	v_mov_b32_e32 v80, v64
	v_mov_b32_e32 v81, v64
	v_mov_b32_e32 v82, v64
	v_mov_b32_e32 v83, v64
	v_mov_b32_e32 v84, v64
	v_mov_b32_e32 v85, v64
	v_mov_b32_e32 v86, v64
	v_mov_b32_e32 v87, v64
	v_mov_b32_e32 v88, v64
	v_mov_b32_e32 v89, v64
	v_mov_b32_e32 v90, v64
	v_mov_b32_e32 v91, v64
	v_mov_b32_e32 v92, v64
	v_mov_b32_e32 v93, v64
	v_mov_b32_e32 v94, v64
	v_mov_b32_e32 v95, v64
	v_mov_b32_e32 v32, v64
	v_mov_b32_e32 v33, v64
	v_mov_b32_e32 v34, v64
	v_mov_b32_e32 v35, v64
	v_mov_b32_e32 v36, v64
	v_mov_b32_e32 v37, v64
	v_mov_b32_e32 v38, v64
	v_mov_b32_e32 v39, v64
	v_mov_b32_e32 v40, v64
	v_mov_b32_e32 v41, v64
	v_mov_b32_e32 v42, v64
	v_mov_b32_e32 v43, v64
	v_mov_b32_e32 v44, v64
	v_mov_b32_e32 v45, v64
	v_mov_b32_e32 v46, v64
	v_mov_b32_e32 v47, v64
	v_mov_b32_e32 v48, v64
	v_mov_b32_e32 v49, v64
	v_mov_b32_e32 v50, v64
	v_mov_b32_e32 v51, v64
	v_mov_b32_e32 v52, v64
	v_mov_b32_e32 v53, v64
	v_mov_b32_e32 v54, v64
	v_mov_b32_e32 v55, v64
	v_mov_b32_e32 v56, v64
	v_mov_b32_e32 v57, v64
	v_mov_b32_e32 v58, v64
	v_mov_b32_e32 v59, v64
	v_mov_b32_e32 v60, v64
	v_mov_b32_e32 v61, v64
	v_mov_b32_e32 v62, v64
	v_mov_b32_e32 v63, v64
	v_mov_b32_e32 v0, v64
	v_mov_b32_e32 v1, v64
	v_mov_b32_e32 v2, v64
	v_mov_b32_e32 v3, v64
	v_mov_b32_e32 v4, v64
	v_mov_b32_e32 v5, v64
	v_mov_b32_e32 v6, v64
	v_mov_b32_e32 v7, v64
	v_mov_b32_e32 v8, v64
	v_mov_b32_e32 v9, v64
	v_mov_b32_e32 v10, v64
	v_mov_b32_e32 v11, v64
	v_mov_b32_e32 v12, v64
	v_mov_b32_e32 v13, v64
	v_mov_b32_e32 v14, v64
	v_mov_b32_e32 v15, v64
	v_mov_b32_e32 v16, v64
	v_mov_b32_e32 v17, v64
	v_mov_b32_e32 v18, v64
	v_mov_b32_e32 v19, v64
	v_mov_b32_e32 v20, v64
	v_mov_b32_e32 v21, v64
	v_mov_b32_e32 v22, v64
	v_mov_b32_e32 v23, v64
	v_mov_b32_e32 v24, v64
	v_mov_b32_e32 v25, v64
	v_mov_b32_e32 v26, v64
	v_mov_b32_e32 v27, v64
	s_waitcnt vmcnt(0)
	v_mov_b32_e32 v28, v64
	v_mov_b32_e32 v29, v64
	v_mov_b32_e32 v30, v64
	v_mov_b32_e32 v31, v64
	s_waitcnt vmcnt(0) lgkmcnt(0)
	s_barrier
	v_readfirstlane_b32 s101, v142
	s_sub_u32 vcc_lo, s12, s10
	s_subb_u32 vcc_hi, s13, s11
	v_mov_b32_e32 v130, v124
	v_mov_b32_e32 v131, 0
	v_lshl_add_u64 v[108:109], v[108:109], 0, vcc
	v_lshl_add_u64 v[110:111], v[110:111], 0, vcc
	v_lshl_add_u64 v[112:113], v[112:113], 0, vcc
	v_lshl_add_u64 v[114:115], v[114:115], 0, vcc
	v_lshl_add_u64 v[96:97], v[96:97], 0, v[130:131]
	v_lshl_add_u64 v[98:99], v[98:99], 0, v[130:131]
	v_lshl_add_u64 v[100:101], v[100:101], 0, v[130:131]
	v_lshl_add_u64 v[102:103], v[102:103], 0, v[130:131]
	v_lshl_add_u64 v[104:105], v[104:105], 0, v[130:131]
	v_lshl_add_u64 v[106:107], v[106:107], 0, v[130:131]
	v_lshl_add_u64 v[108:109], v[108:109], 0, v[130:131]
	v_lshl_add_u64 v[110:111], v[110:111], 0, v[130:131]
	v_lshl_add_u64 v[112:113], v[112:113], 0, v[130:131]
	v_lshl_add_u64 v[114:115], v[114:115], 0, v[130:131]
	v_add_u32_e32 v116, v155, v184
	v_add_u32_e32 v117, v155, v185
	v_add_u32_e32 v118, v155, v186
	v_add_u32_e32 v119, v155, v187
	v_add_u32_e32 v120, v182, v184
	v_add_u32_e32 v121, v182, v185
	v_add_u32_e32 v122, v182, v186
	v_add_u32_e32 v123, v182, v187
	v_add_u32_e32 v120, 0x8000, v120
	v_add_u32_e32 v121, 0x8000, v121
	v_add_u32_e32 v122, 0x8000, v122
	v_add_u32_e32 v123, 0x8000, v123
	v_lshl_add_u64 v[96:97], v[96:97], 0, s[2:3]
	v_lshl_add_u64 v[98:99], v[98:99], 0, s[2:3]
	v_lshl_add_u64 v[100:101], v[100:101], 0, s[2:3]
	v_lshl_add_u64 v[102:103], v[102:103], 0, s[2:3]
	v_lshl_add_u64 v[104:105], v[104:105], 0, s[2:3]
	v_lshl_add_u64 v[106:107], v[106:107], 0, s[2:3]
	v_lshl_add_u64 v[108:109], v[108:109], 0, s[2:3]
	v_lshl_add_u64 v[110:111], v[110:111], 0, s[2:3]
	v_lshl_add_u64 v[112:113], v[112:113], 0, s[2:3]
	v_lshl_add_u64 v[114:115], v[114:115], 0, s[2:3]
	ds_read_b128 v[192:195], v116 offset:0
	ds_read_b128 v[204:207], v120 offset:16384
	ds_read_b128 v[208:211], v120 offset:20480
	ds_read_b128 v[196:199], v116 offset:4096
	ds_read_b128 v[200:203], v116 offset:8192
	s_add_u32 m0, s101, 0x6000
	s_nop 0
	global_load_lds_dwordx4 v[96:97], off
	v_lshl_add_u64 v[96:97], v[96:97], 0, s[2:3]
	s_add_u32 m0, s101, 0x7000
	s_nop 0
	global_load_lds_dwordx4 v[98:99], off
	v_lshl_add_u64 v[98:99], v[98:99], 0, s[2:3]
	s_add_u32 m0, s101, 0x8000
	s_nop 0
	global_load_lds_dwordx4 v[100:101], off
	v_lshl_add_u64 v[100:101], v[100:101], 0, s[2:3]
	s_add_u32 m0, s101, 0x9000
	s_nop 0
	global_load_lds_dwordx4 v[102:103], off
	v_lshl_add_u64 v[102:103], v[102:103], 0, s[2:3]
	s_add_u32 m0, s101, 0xa000
	s_nop 0
	global_load_lds_dwordx4 v[104:105], off
	v_lshl_add_u64 v[104:105], v[104:105], 0, s[2:3]
	s_add_u32 m0, s101, 0xb000
	s_nop 0
	global_load_lds_dwordx4 v[106:107], off
	v_lshl_add_u64 v[106:107], v[106:107], 0, s[2:3]
	s_mov_b32 s100, 7
.Lgu2_loop:
	s_waitcnt lgkmcnt(3)
	v_mfma_f32_32x32x16_bf16 v[64:79], v[192:195], v[204:207], v[64:79]
	s_add_u32 m0, s101, 0x10000
	ds_read_b128 v[212:215], v117 offset:0
	global_load_lds_dwordx4 v[108:109], off
	v_lshl_add_u64 v[108:109], v[108:109], 0, s[2:3]
	s_waitcnt lgkmcnt(3)
	v_mfma_f32_32x32x16_bf16 v[80:95], v[192:195], v[208:211], v[80:95]
	s_add_u32 m0, s101, 0x11000
	ds_read_b128 v[224:227], v121 offset:16384
	global_load_lds_dwordx4 v[110:111], off
	v_lshl_add_u64 v[110:111], v[110:111], 0, s[2:3]
	s_waitcnt lgkmcnt(3)
	v_mfma_f32_32x32x16_bf16 v[32:47], v[196:199], v[204:207], v[32:47]
	s_add_u32 m0, s101, 0x12000
	ds_read_b128 v[228:231], v121 offset:20480
	global_load_lds_dwordx4 v[112:113], off
	v_lshl_add_u64 v[112:113], v[112:113], 0, s[2:3]
	v_mfma_f32_32x32x16_bf16 v[48:63], v[196:199], v[208:211], v[48:63]
	s_add_u32 m0, s101, 0x13000
	ds_read_b128 v[216:219], v117 offset:4096
	global_load_lds_dwordx4 v[114:115], off
	v_lshl_add_u64 v[114:115], v[114:115], 0, s[2:3]
	s_waitcnt lgkmcnt(4)
	v_mfma_f32_32x32x16_bf16 v[0:15], v[200:203], v[204:207], v[0:15]
	ds_read_b128 v[220:223], v117 offset:8192
	v_mfma_f32_32x32x16_bf16 v[16:31], v[200:203], v[208:211], v[16:31]
	s_waitcnt lgkmcnt(3)
	v_mfma_f32_32x32x16_bf16 v[64:79], v[212:215], v[224:227], v[64:79]
	ds_read_b128 v[192:195], v118 offset:0
	s_waitcnt lgkmcnt(3)
	v_mfma_f32_32x32x16_bf16 v[80:95], v[212:215], v[228:231], v[80:95]
	ds_read_b128 v[204:207], v122 offset:16384
	s_waitcnt lgkmcnt(3)
	v_mfma_f32_32x32x16_bf16 v[32:47], v[216:219], v[224:227], v[32:47]
	ds_read_b128 v[208:211], v122 offset:20480
	v_mfma_f32_32x32x16_bf16 v[48:63], v[216:219], v[228:231], v[48:63]
	ds_read_b128 v[196:199], v118 offset:4096
	s_waitcnt lgkmcnt(4)
	v_mfma_f32_32x32x16_bf16 v[0:15], v[220:223], v[224:227], v[0:15]
	ds_read_b128 v[200:203], v118 offset:8192
	v_mfma_f32_32x32x16_bf16 v[16:31], v[220:223], v[228:231], v[16:31]
	s_waitcnt lgkmcnt(3)
	v_mfma_f32_32x32x16_bf16 v[64:79], v[192:195], v[204:207], v[64:79]
	ds_read_b128 v[212:215], v119 offset:0
	s_waitcnt lgkmcnt(3)
	v_mfma_f32_32x32x16_bf16 v[80:95], v[192:195], v[208:211], v[80:95]
	ds_read_b128 v[224:227], v123 offset:16384
	s_waitcnt lgkmcnt(3)
	v_mfma_f32_32x32x16_bf16 v[32:47], v[196:199], v[204:207], v[32:47]
	ds_read_b128 v[228:231], v123 offset:20480
	v_mfma_f32_32x32x16_bf16 v[48:63], v[196:199], v[208:211], v[48:63]
	ds_read_b128 v[216:219], v119 offset:4096
	s_waitcnt lgkmcnt(4)
	v_mfma_f32_32x32x16_bf16 v[0:15], v[200:203], v[204:207], v[0:15]
	ds_read_b128 v[220:223], v119 offset:8192
	v_mfma_f32_32x32x16_bf16 v[16:31], v[200:203], v[208:211], v[16:31]
	s_waitcnt vmcnt(0) lgkmcnt(0)
	s_barrier
	v_mfma_f32_32x32x16_bf16 v[64:79], v[212:215], v[224:227], v[64:79]
	s_add_u32 m0, s101, 0x0
	ds_read_b128 v[192:195], v116 offset:24576
	global_load_lds_dwordx4 v[96:97], off
	v_lshl_add_u64 v[96:97], v[96:97], 0, s[2:3]
	v_mfma_f32_32x32x16_bf16 v[80:95], v[212:215], v[228:231], v[80:95]
	s_add_u32 m0, s101, 0x1000
	ds_read_b128 v[204:207], v120 offset:32768
	global_load_lds_dwordx4 v[98:99], off
	v_lshl_add_u64 v[98:99], v[98:99], 0, s[2:3]
	v_mfma_f32_32x32x16_bf16 v[32:47], v[216:219], v[224:227], v[32:47]
	s_add_u32 m0, s101, 0x2000
	ds_read_b128 v[208:211], v120 offset:36864
	global_load_lds_dwordx4 v[100:101], off
	v_lshl_add_u64 v[100:101], v[100:101], 0, s[2:3]
	v_mfma_f32_32x32x16_bf16 v[48:63], v[216:219], v[228:231], v[48:63]
	s_add_u32 m0, s101, 0x3000
	ds_read_b128 v[196:199], v116 offset:28672
	global_load_lds_dwordx4 v[102:103], off
	v_lshl_add_u64 v[102:103], v[102:103], 0, s[2:3]
	v_mfma_f32_32x32x16_bf16 v[0:15], v[220:223], v[224:227], v[0:15]
	s_add_u32 m0, s101, 0x4000
	ds_read_b128 v[200:203], v116 offset:32768
	global_load_lds_dwordx4 v[104:105], off
	v_lshl_add_u64 v[104:105], v[104:105], 0, s[2:3]
	v_mfma_f32_32x32x16_bf16 v[16:31], v[220:223], v[228:231], v[16:31]
	s_add_u32 m0, s101, 0x5000
	s_nop 0
	global_load_lds_dwordx4 v[106:107], off
	v_lshl_add_u64 v[106:107], v[106:107], 0, s[2:3]
	s_waitcnt lgkmcnt(3)
	v_mfma_f32_32x32x16_bf16 v[64:79], v[192:195], v[204:207], v[64:79]
	s_add_u32 m0, s101, 0xc000
	ds_read_b128 v[212:215], v117 offset:24576
	global_load_lds_dwordx4 v[108:109], off
	v_lshl_add_u64 v[108:109], v[108:109], 0, s[2:3]
	s_waitcnt lgkmcnt(3)
	v_mfma_f32_32x32x16_bf16 v[80:95], v[192:195], v[208:211], v[80:95]
	s_add_u32 m0, s101, 0xd000
	ds_read_b128 v[224:227], v121 offset:32768
	global_load_lds_dwordx4 v[110:111], off
	v_lshl_add_u64 v[110:111], v[110:111], 0, s[2:3]
	s_waitcnt lgkmcnt(3)
	v_mfma_f32_32x32x16_bf16 v[32:47], v[196:199], v[204:207], v[32:47]
	s_add_u32 m0, s101, 0xe000
	ds_read_b128 v[228:231], v121 offset:36864
	global_load_lds_dwordx4 v[112:113], off
	v_lshl_add_u64 v[112:113], v[112:113], 0, s[2:3]
	v_mfma_f32_32x32x16_bf16 v[48:63], v[196:199], v[208:211], v[48:63]
	s_add_u32 m0, s101, 0xf000
	ds_read_b128 v[216:219], v117 offset:28672
	global_load_lds_dwordx4 v[114:115], off
	v_lshl_add_u64 v[114:115], v[114:115], 0, s[2:3]
	s_waitcnt lgkmcnt(4)
	v_mfma_f32_32x32x16_bf16 v[0:15], v[200:203], v[204:207], v[0:15]
	ds_read_b128 v[220:223], v117 offset:32768
	v_mfma_f32_32x32x16_bf16 v[16:31], v[200:203], v[208:211], v[16:31]
	s_waitcnt lgkmcnt(3)
	v_mfma_f32_32x32x16_bf16 v[64:79], v[212:215], v[224:227], v[64:79]
	ds_read_b128 v[192:195], v118 offset:24576
	s_waitcnt lgkmcnt(3)
	v_mfma_f32_32x32x16_bf16 v[80:95], v[212:215], v[228:231], v[80:95]
	ds_read_b128 v[204:207], v122 offset:32768
	s_waitcnt lgkmcnt(3)
	v_mfma_f32_32x32x16_bf16 v[32:47], v[216:219], v[224:227], v[32:47]
	ds_read_b128 v[208:211], v122 offset:36864
	v_mfma_f32_32x32x16_bf16 v[48:63], v[216:219], v[228:231], v[48:63]
	ds_read_b128 v[196:199], v118 offset:28672
	s_waitcnt lgkmcnt(4)
	v_mfma_f32_32x32x16_bf16 v[0:15], v[220:223], v[224:227], v[0:15]
	ds_read_b128 v[200:203], v118 offset:32768
	v_mfma_f32_32x32x16_bf16 v[16:31], v[220:223], v[228:231], v[16:31]
	s_waitcnt lgkmcnt(3)
	v_mfma_f32_32x32x16_bf16 v[64:79], v[192:195], v[204:207], v[64:79]
	ds_read_b128 v[212:215], v119 offset:24576
	s_waitcnt lgkmcnt(3)
	v_mfma_f32_32x32x16_bf16 v[80:95], v[192:195], v[208:211], v[80:95]
	ds_read_b128 v[224:227], v123 offset:32768
	s_waitcnt lgkmcnt(3)
	v_mfma_f32_32x32x16_bf16 v[32:47], v[196:199], v[204:207], v[32:47]
	ds_read_b128 v[228:231], v123 offset:36864
	v_mfma_f32_32x32x16_bf16 v[48:63], v[196:199], v[208:211], v[48:63]
	ds_read_b128 v[216:219], v119 offset:28672
	s_waitcnt lgkmcnt(4)
	v_mfma_f32_32x32x16_bf16 v[0:15], v[200:203], v[204:207], v[0:15]
	ds_read_b128 v[220:223], v119 offset:32768
	v_mfma_f32_32x32x16_bf16 v[16:31], v[200:203], v[208:211], v[16:31]
	s_waitcnt vmcnt(0) lgkmcnt(0)
	s_barrier
	v_mfma_f32_32x32x16_bf16 v[64:79], v[212:215], v[224:227], v[64:79]
	s_add_u32 m0, s101, 0x6000
	ds_read_b128 v[192:195], v116 offset:0
	global_load_lds_dwordx4 v[96:97], off
	v_lshl_add_u64 v[96:97], v[96:97], 0, s[2:3]
	v_mfma_f32_32x32x16_bf16 v[80:95], v[212:215], v[228:231], v[80:95]
	s_add_u32 m0, s101, 0x7000
	ds_read_b128 v[204:207], v120 offset:16384
	global_load_lds_dwordx4 v[98:99], off
	v_lshl_add_u64 v[98:99], v[98:99], 0, s[2:3]
	v_mfma_f32_32x32x16_bf16 v[32:47], v[216:219], v[224:227], v[32:47]
	s_add_u32 m0, s101, 0x8000
	ds_read_b128 v[208:211], v120 offset:20480
	global_load_lds_dwordx4 v[100:101], off
	v_lshl_add_u64 v[100:101], v[100:101], 0, s[2:3]
	v_mfma_f32_32x32x16_bf16 v[48:63], v[216:219], v[228:231], v[48:63]
	s_add_u32 m0, s101, 0x9000
	ds_read_b128 v[196:199], v116 offset:4096
	global_load_lds_dwordx4 v[102:103], off
	v_lshl_add_u64 v[102:103], v[102:103], 0, s[2:3]
	v_mfma_f32_32x32x16_bf16 v[0:15], v[220:223], v[224:227], v[0:15]
	s_add_u32 m0, s101, 0xa000
	ds_read_b128 v[200:203], v116 offset:8192
	global_load_lds_dwordx4 v[104:105], off
	v_lshl_add_u64 v[104:105], v[104:105], 0, s[2:3]
	v_mfma_f32_32x32x16_bf16 v[16:31], v[220:223], v[228:231], v[16:31]
	s_add_u32 m0, s101, 0xb000
	s_nop 0
	global_load_lds_dwordx4 v[106:107], off
	v_lshl_add_u64 v[106:107], v[106:107], 0, s[2:3]
	s_add_i32 s100, s100, -1
	s_cmp_lg_u32 s100, 0
	s_cbranch_scc1 .Lgu2_loop
	s_waitcnt lgkmcnt(3)
	v_mfma_f32_32x32x16_bf16 v[64:79], v[192:195], v[204:207], v[64:79]
	s_add_u32 m0, s101, 0x10000
	ds_read_b128 v[212:215], v117 offset:0
	global_load_lds_dwordx4 v[108:109], off
	v_lshl_add_u64 v[108:109], v[108:109], 0, s[2:3]
	s_waitcnt lgkmcnt(3)
	v_mfma_f32_32x32x16_bf16 v[80:95], v[192:195], v[208:211], v[80:95]
	s_add_u32 m0, s101, 0x11000
	ds_read_b128 v[224:227], v121 offset:16384
	global_load_lds_dwordx4 v[110:111], off
	v_lshl_add_u64 v[110:111], v[110:111], 0, s[2:3]
	s_waitcnt lgkmcnt(3)
	v_mfma_f32_32x32x16_bf16 v[32:47], v[196:199], v[204:207], v[32:47]
	s_add_u32 m0, s101, 0x12000
	ds_read_b128 v[228:231], v121 offset:20480
	global_load_lds_dwordx4 v[112:113], off
	v_lshl_add_u64 v[112:113], v[112:113], 0, s[2:3]
	v_mfma_f32_32x32x16_bf16 v[48:63], v[196:199], v[208:211], v[48:63]
	s_add_u32 m0, s101, 0x13000
	ds_read_b128 v[216:219], v117 offset:4096
	global_load_lds_dwordx4 v[114:115], off
	v_lshl_add_u64 v[114:115], v[114:115], 0, s[2:3]
	s_waitcnt lgkmcnt(4)
	v_mfma_f32_32x32x16_bf16 v[0:15], v[200:203], v[204:207], v[0:15]
	ds_read_b128 v[220:223], v117 offset:8192
	v_mfma_f32_32x32x16_bf16 v[16:31], v[200:203], v[208:211], v[16:31]
	s_waitcnt lgkmcnt(3)
	v_mfma_f32_32x32x16_bf16 v[64:79], v[212:215], v[224:227], v[64:79]
	ds_read_b128 v[192:195], v118 offset:0
	s_waitcnt lgkmcnt(3)
	v_mfma_f32_32x32x16_bf16 v[80:95], v[212:215], v[228:231], v[80:95]
	ds_read_b128 v[204:207], v122 offset:16384
	s_waitcnt lgkmcnt(3)
	v_mfma_f32_32x32x16_bf16 v[32:47], v[216:219], v[224:227], v[32:47]
	ds_read_b128 v[208:211], v122 offset:20480
	v_mfma_f32_32x32x16_bf16 v[48:63], v[216:219], v[228:231], v[48:63]
	ds_read_b128 v[196:199], v118 offset:4096
	s_waitcnt lgkmcnt(4)
	v_mfma_f32_32x32x16_bf16 v[0:15], v[220:223], v[224:227], v[0:15]
	ds_read_b128 v[200:203], v118 offset:8192
	v_mfma_f32_32x32x16_bf16 v[16:31], v[220:223], v[228:231], v[16:31]
	s_waitcnt lgkmcnt(3)
	v_mfma_f32_32x32x16_bf16 v[64:79], v[192:195], v[204:207], v[64:79]
	ds_read_b128 v[212:215], v119 offset:0
	s_waitcnt lgkmcnt(3)
	v_mfma_f32_32x32x16_bf16 v[80:95], v[192:195], v[208:211], v[80:95]
	ds_read_b128 v[224:227], v123 offset:16384
	s_waitcnt lgkmcnt(3)
	v_mfma_f32_32x32x16_bf16 v[32:47], v[196:199], v[204:207], v[32:47]
	ds_read_b128 v[228:231], v123 offset:20480
	v_mfma_f32_32x32x16_bf16 v[48:63], v[196:199], v[208:211], v[48:63]
	ds_read_b128 v[216:219], v119 offset:4096
	s_waitcnt lgkmcnt(4)
	v_mfma_f32_32x32x16_bf16 v[0:15], v[200:203], v[204:207], v[0:15]
	ds_read_b128 v[220:223], v119 offset:8192
	v_mfma_f32_32x32x16_bf16 v[16:31], v[200:203], v[208:211], v[16:31]
	s_waitcnt vmcnt(0) lgkmcnt(0)
	s_barrier
	v_mfma_f32_32x32x16_bf16 v[64:79], v[212:215], v[224:227], v[64:79]
	ds_read_b128 v[192:195], v116 offset:24576
	v_mfma_f32_32x32x16_bf16 v[80:95], v[212:215], v[228:231], v[80:95]
	ds_read_b128 v[204:207], v120 offset:32768
	v_mfma_f32_32x32x16_bf16 v[32:47], v[216:219], v[224:227], v[32:47]
	ds_read_b128 v[208:211], v120 offset:36864
	v_mfma_f32_32x32x16_bf16 v[48:63], v[216:219], v[228:231], v[48:63]
	ds_read_b128 v[196:199], v116 offset:28672
	v_mfma_f32_32x32x16_bf16 v[0:15], v[220:223], v[224:227], v[0:15]
	ds_read_b128 v[200:203], v116 offset:32768
	v_mfma_f32_32x32x16_bf16 v[16:31], v[220:223], v[228:231], v[16:31]
	s_waitcnt lgkmcnt(3)
	v_mfma_f32_32x32x16_bf16 v[64:79], v[192:195], v[204:207], v[64:79]
	ds_read_b128 v[212:215], v117 offset:24576
	s_waitcnt lgkmcnt(3)
	v_mfma_f32_32x32x16_bf16 v[80:95], v[192:195], v[208:211], v[80:95]
	ds_read_b128 v[224:227], v121 offset:32768
	s_waitcnt lgkmcnt(3)
	v_mfma_f32_32x32x16_bf16 v[32:47], v[196:199], v[204:207], v[32:47]
	ds_read_b128 v[228:231], v121 offset:36864
	v_mfma_f32_32x32x16_bf16 v[48:63], v[196:199], v[208:211], v[48:63]
	ds_read_b128 v[216:219], v117 offset:28672
	s_waitcnt lgkmcnt(4)
	v_mfma_f32_32x32x16_bf16 v[0:15], v[200:203], v[204:207], v[0:15]
	ds_read_b128 v[220:223], v117 offset:32768
	v_mfma_f32_32x32x16_bf16 v[16:31], v[200:203], v[208:211], v[16:31]
	s_waitcnt lgkmcnt(3)
	v_mfma_f32_32x32x16_bf16 v[64:79], v[212:215], v[224:227], v[64:79]
	ds_read_b128 v[192:195], v118 offset:24576
	s_waitcnt lgkmcnt(3)
	v_mfma_f32_32x32x16_bf16 v[80:95], v[212:215], v[228:231], v[80:95]
	ds_read_b128 v[204:207], v122 offset:32768
	s_waitcnt lgkmcnt(3)
	v_mfma_f32_32x32x16_bf16 v[32:47], v[216:219], v[224:227], v[32:47]
	ds_read_b128 v[208:211], v122 offset:36864
	v_mfma_f32_32x32x16_bf16 v[48:63], v[216:219], v[228:231], v[48:63]
	ds_read_b128 v[196:199], v118 offset:28672
	s_waitcnt lgkmcnt(4)
	v_mfma_f32_32x32x16_bf16 v[0:15], v[220:223], v[224:227], v[0:15]
	ds_read_b128 v[200:203], v118 offset:32768
	v_mfma_f32_32x32x16_bf16 v[16:31], v[220:223], v[228:231], v[16:31]
	s_waitcnt lgkmcnt(3)
	v_mfma_f32_32x32x16_bf16 v[64:79], v[192:195], v[204:207], v[64:79]
	ds_read_b128 v[212:215], v119 offset:24576
	s_waitcnt lgkmcnt(3)
	v_mfma_f32_32x32x16_bf16 v[80:95], v[192:195], v[208:211], v[80:95]
	ds_read_b128 v[224:227], v123 offset:32768
	s_waitcnt lgkmcnt(3)
	v_mfma_f32_32x32x16_bf16 v[32:47], v[196:199], v[204:207], v[32:47]
	ds_read_b128 v[228:231], v123 offset:36864
	v_mfma_f32_32x32x16_bf16 v[48:63], v[196:199], v[208:211], v[48:63]
	ds_read_b128 v[216:219], v119 offset:28672
	s_waitcnt lgkmcnt(4)
	v_mfma_f32_32x32x16_bf16 v[0:15], v[200:203], v[204:207], v[0:15]
	ds_read_b128 v[220:223], v119 offset:32768
	v_mfma_f32_32x32x16_bf16 v[16:31], v[200:203], v[208:211], v[16:31]
	s_waitcnt vmcnt(0) lgkmcnt(0)
	s_barrier
	v_mfma_f32_32x32x16_bf16 v[64:79], v[212:215], v[224:227], v[64:79]
	v_mfma_f32_32x32x16_bf16 v[80:95], v[212:215], v[228:231], v[80:95]
	v_mfma_f32_32x32x16_bf16 v[32:47], v[216:219], v[224:227], v[32:47]
	v_mfma_f32_32x32x16_bf16 v[48:63], v[216:219], v[228:231], v[48:63]
	v_mfma_f32_32x32x16_bf16 v[0:15], v[220:223], v[224:227], v[0:15]
	v_mfma_f32_32x32x16_bf16 v[16:31], v[220:223], v[228:231], v[16:31]
	s_nop 7
	s_nop 7
	s_branch .LBB0_82

.LBB0_1134:
	s_waitcnt vmcnt(7)
	v_mov_b32_e32 v18, v127
	s_ashr_i32 s0, s43, 31
	s_lshr_b32 s0, s0, 26
	v_ashrrev_i32_e32 v19, 6, v18
	s_waitcnt vmcnt(6)
	v_bfe_u32 v21, v18, 3, 3
	v_lshlrev_b32_e32 v22, 3, v19
	s_add_i32 s0, s43, s0
	v_or_b32_e32 v8, v22, v21
	v_lshrrev_b32_e32 v9, 30, v19
	s_ashr_i32 s7, s0, 6
	s_and_b32 s0, s0, 0x7ffffc0
	v_lshrrev_b32_e32 v23, 1, v8
	v_add_u32_e32 v9, v19, v9
	s_sub_i32 s4, s43, s0
	s_lshl_b32 s5, s7, 7
	v_xor_b32_e32 v4, v23, v18
	s_waitcnt vmcnt(5)
	v_ashrrev_i32_e32 v24, 2, v9
	s_mulk_i32 s4, 0x60
	v_and_b32_e32 v20, 63, v18
	v_readlane_b32 s10, v238, 6
	v_lshlrev_b32_e32 v4, 4, v4
	v_add_u32_e32 v12, 32, v8
	v_add_u32_e32 v14, 64, v8
	v_mul_i32_i24_e32 v9, 4, v24
	v_add_u32_e32 v16, s5, v8
	v_add_u32_e32 v0, s4, v8
	v_and_b32_e32 v124, 0x70, v4
	v_add_u32_e32 v4, s4, v12
	v_add_u32_e32 v6, s4, v14
	v_sub_u32_e32 v76, v19, v9
	v_mad_i64_i32 v[8:9], s[0:1], v16, s10, 0
	v_add_u32_e32 v12, s5, v12
	v_add_u32_e32 v14, s5, v14
	v_add_u32_e32 v16, 0x60, v16
	v_lshlrev_b32_e32 v80, 10, v19
	v_lshlrev_b32_e32 v81, 4, v20
	v_mad_i64_i32 v[0:1], s[0:1], v0, s10, 0
	v_mad_i64_i32 v[4:5], s[0:1], v4, s10, 0
	v_mad_i64_i32 v[6:7], s[0:1], v6, s10, 0
	v_mad_i64_i32 v[12:13], s[0:1], v12, s10, 0
	v_mad_i64_i32 v[14:15], s[0:1], v14, s10, 0
	v_mad_i64_i32 v[16:17], s[0:1], v16, s10, 0
	v_or_b32_e32 v19, v80, v81
	v_lshl_add_u64 v[0:1], v[0:1], 1, s[48:49]
	v_readfirstlane_b32 s0, v19
	v_lshl_add_u64 v[0:1], v[0:1], 0, v[124:125]
	s_mov_b32 m0, s0
	v_lshl_add_u64 v[4:5], v[4:5], 1, s[48:49]
	global_load_lds_dwordx4 v[0:1], off
	v_add_u32_e32 v0, 0x1000, v19
	v_readlane_b32 s8, v238, 8
	v_readfirstlane_b32 s0, v0
	v_add_u32_e32 v0, 0x2000, v19
	v_lshl_add_u64 v[4:5], v[4:5], 0, v[124:125]
	v_lshl_add_u64 v[6:7], v[6:7], 1, s[48:49]
	v_readlane_b32 s9, v238, 9
	v_add_u32_e32 v20, 0x6000, v19
	s_mov_b32 m0, s0
	v_readfirstlane_b32 s0, v0
	v_lshl_add_u64 v[6:7], v[6:7], 0, v[124:125]
	v_lshl_add_u64 v[8:9], v[8:9], 1, s[8:9]
	global_load_lds_dwordx4 v[4:5], off
	s_mov_b32 m0, s0
	v_readfirstlane_b32 s0, v20
	v_add_u32_e32 v0, 0x7000, v19
	v_lshl_add_u64 v[8:9], v[8:9], 0, v[124:125]
	v_lshl_add_u64 v[12:13], v[12:13], 1, s[8:9]
	global_load_lds_dwordx4 v[6:7], off
	s_mov_b32 m0, s0
	v_readfirstlane_b32 s0, v0
	v_add_u32_e32 v0, 0x8000, v19
	v_lshl_add_u64 v[12:13], v[12:13], 0, v[124:125]
	v_lshl_add_u64 v[14:15], v[14:15], 1, s[8:9]
	global_load_lds_dwordx4 v[8:9], off
	s_mov_b32 m0, s0
	v_readfirstlane_b32 s0, v0
	v_add_u32_e32 v0, 0x9000, v19
	v_lshl_add_u64 v[14:15], v[14:15], 0, v[124:125]
	v_lshl_add_u64 v[16:17], v[16:17], 1, s[8:9]
	global_load_lds_dwordx4 v[12:13], off
	s_mov_b32 m0, s0
	v_readfirstlane_b32 s0, v0
	v_lshl_add_u64 v[16:17], v[16:17], 0, v[124:125]
	global_load_lds_dwordx4 v[14:15], off
	s_mov_b32 m0, s0
	v_and_b32_e32 v78, 31, v18
	global_load_lds_dwordx4 v[16:17], off
	v_mul_i32_i24_e32 v79, 0x60, v24
	v_or_b32_e32 v1, v79, v78
	v_lshrrev_b32_e32 v25, 1, v18
	v_lshlrev_b32_e32 v82, 7, v1
	v_lshlrev_b32_e32 v1, 7, v78
	v_bfe_u32 v77, v18, 5, 1
	v_bfe_u32 v0, v18, 1, 3
	v_lshl_or_b32 v83, v76, 12, v1
	v_bitop3_b32 v1, v77, v25, 7 bitop3:0x78
	v_lshlrev_b32_e32 v84, 4, v1
	v_bitop3_b32 v1, v77, v0, 2 bitop3:0x36
	v_lshlrev_b32_e32 v85, 4, v1
	v_bitop3_b32 v1, v77, v0, 4 bitop3:0x36
	v_bitop3_b32 v0, v77, v0, 6 bitop3:0x36
	v_mov_b64_e32 v[10:11], s[8:9]
	v_lshlrev_b32_e32 v87, 4, v0
	v_bitop3_b32 v0, v23, 7, v18 bitop3:0x48
	s_mul_i32 s8, s43, 0x60
	v_lshlrev_b32_e32 v124, 4, v0
	v_or_b32_e32 v0, s8, v21
	v_add_u32_e32 v0, v0, v22
	s_mulk_i32 s7, 0x1800
	v_mov_b64_e32 v[2:3], s[48:49]
	v_subrev_u32_e32 v0, s7, v0
	v_readlane_b32 s9, v238, 18
	v_lshlrev_b32_e32 v86, 4, v1
	s_waitcnt vmcnt(0)
	v_mov_b32_e32 v32, 0
	v_mad_i64_i32 v[48:49], s[0:1], s9, v0, v[2:3]
	v_or_b32_e32 v0, 32, v21
	v_add3_u32 v1, v0, s8, v22
	v_subrev_u32_e32 v1, s7, v1
	v_mad_i64_i32 v[50:51], s[0:1], s9, v1, v[2:3]
	v_or_b32_e32 v1, 64, v21
	v_add3_u32 v4, v1, s8, v22
	v_or_b32_e32 v0, s5, v0
	v_subrev_u32_e32 v4, s7, v4
	v_add_u32_e32 v0, v0, v22
	v_mad_i64_i32 v[52:53], s[0:1], s9, v4, v[2:3]
	v_or_b32_e32 v2, s5, v21
	v_mad_i64_i32 v[56:57], s[0:1], s9, v0, v[10:11]
	v_or_b32_e32 v0, s5, v1
	v_add_u32_e32 v2, v2, v22
	v_add_u32_e32 v0, v0, v22
	v_mad_i64_i32 v[58:59], s[0:1], s9, v0, v[10:11]
	v_add_u32_e32 v0, 0x60, v2
	s_mov_b32 s6, 2
	v_mad_i64_i32 v[54:55], s[0:1], s9, v2, v[10:11]
	v_mad_i64_i32 v[60:61], s[0:1], s9, v0, v[10:11]
	v_mov_b32_e32 v33, v32
	v_mov_b32_e32 v34, v32
	v_mov_b32_e32 v35, v32
	v_mov_b32_e32 v36, v32
	v_mov_b32_e32 v37, v32
	v_mov_b32_e32 v38, v32
	v_mov_b32_e32 v39, v32
	v_mov_b32_e32 v40, v32
	v_mov_b32_e32 v41, v32
	v_mov_b32_e32 v42, v32
	v_mov_b32_e32 v43, v32
	v_mov_b32_e32 v44, v32
	v_mov_b32_e32 v45, v32
	v_mov_b32_e32 v46, v32
	v_mov_b32_e32 v47, v32
	v_mov_b32_e32 v16, v32
	v_mov_b32_e32 v17, v32
	v_mov_b32_e32 v18, v32
	v_mov_b32_e32 v19, v32
	v_mov_b32_e32 v20, v32
	v_mov_b32_e32 v21, v32
	v_mov_b32_e32 v22, v32
	v_mov_b32_e32 v23, v32
	v_mov_b32_e32 v24, v32
	v_mov_b32_e32 v25, v32
	v_mov_b32_e32 v26, v32
	v_mov_b32_e32 v27, v32
	s_waitcnt vmcnt(0)
	v_mov_b32_e32 v28, v32
	v_mov_b32_e32 v29, v32
	v_mov_b32_e32 v30, v32
	v_mov_b32_e32 v31, v32
	v_mov_b32_e32 v0, v32
	v_mov_b32_e32 v1, v32
	v_mov_b32_e32 v2, v32
	v_mov_b32_e32 v3, v32
	v_mov_b32_e32 v4, v32
	v_mov_b32_e32 v5, v32
	v_mov_b32_e32 v6, v32
	v_mov_b32_e32 v7, v32
	v_mov_b32_e32 v8, v32
	v_mov_b32_e32 v9, v32
	v_mov_b32_e32 v10, v32
	v_mov_b32_e32 v11, v32
	v_mov_b32_e32 v12, v32
	v_mov_b32_e32 v13, v32
	v_mov_b32_e32 v14, v32
	v_mov_b32_e32 v15, v32
	s_waitcnt lgkmcnt(0)
	s_barrier
	v_add_u32_e32 v134, v80, v81
	s_nop 0
	v_readfirstlane_b32 s101, v134
	v_mov_b32_e32 v136, v124
	v_mov_b32_e32 v137, 0
	v_lshl_add_u64 v[48:49], v[48:49], 0, v[136:137]
	v_lshl_add_u64 v[50:51], v[50:51], 0, v[136:137]
	v_lshl_add_u64 v[52:53], v[52:53], 0, v[136:137]
	v_lshl_add_u64 v[54:55], v[54:55], 0, v[136:137]
	v_lshl_add_u64 v[56:57], v[56:57], 0, v[136:137]
	v_lshl_add_u64 v[58:59], v[58:59], 0, v[136:137]
	v_lshl_add_u64 v[60:61], v[60:61], 0, v[136:137]
	v_add_u32_e32 v120, v82, v84
	v_add_u32_e32 v121, v82, v85
	v_add_u32_e32 v122, v82, v86
	v_add_u32_e32 v123, v82, v87
	v_add_u32_e32 v130, v83, v84
	v_add_u32_e32 v131, v83, v85
	v_add_u32_e32 v132, v83, v86
	v_add_u32_e32 v133, v83, v87
	v_lshl_add_u64 v[48:49], v[48:49], 0, s[2:3]
	v_lshl_add_u64 v[50:51], v[50:51], 0, s[2:3]
	v_lshl_add_u64 v[52:53], v[52:53], 0, s[2:3]
	v_lshl_add_u64 v[54:55], v[54:55], 0, s[2:3]
	v_lshl_add_u64 v[56:57], v[56:57], 0, s[2:3]
	v_lshl_add_u64 v[58:59], v[58:59], 0, s[2:3]
	v_lshl_add_u64 v[60:61], v[60:61], 0, s[2:3]
	ds_read_b128 v[88:91], v120 offset:0
	ds_read_b128 v[100:103], v130 offset:24576
	ds_read_b128 v[92:95], v120 offset:4096
	ds_read_b128 v[96:99], v120 offset:8192
	s_add_u32 m0, s101, 0x3000
	s_nop 0
	global_load_lds_dwordx4 v[48:49], off
	v_lshl_add_u64 v[48:49], v[48:49], 0, s[2:3]
	s_add_u32 m0, s101, 0x4000
	s_nop 0
	global_load_lds_dwordx4 v[50:51], off
	v_lshl_add_u64 v[50:51], v[50:51], 0, s[2:3]
	s_add_u32 m0, s101, 0x5000
	s_nop 0
	global_load_lds_dwordx4 v[52:53], off
	v_lshl_add_u64 v[52:53], v[52:53], 0, s[2:3]
	s_add_u32 m0, s101, 0xa000
	s_nop 0
	global_load_lds_dwordx4 v[54:55], off
	v_lshl_add_u64 v[54:55], v[54:55], 0, s[2:3]
	s_lshr_b32 s100, s42, 1
	s_add_i32 s100, s100, -1
.Lrsd_loop:
	s_waitcnt lgkmcnt(2)
	v_mfma_f32_32x32x16_bf16 v[32:47], v[88:91], v[100:103], v[32:47]
	s_add_u32 m0, s101, 0xb000
	ds_read_b128 v[104:107], v121 offset:0
	global_load_lds_dwordx4 v[56:57], off
	v_lshl_add_u64 v[56:57], v[56:57], 0, s[2:3]
	s_waitcnt lgkmcnt(2)
	v_mfma_f32_32x32x16_bf16 v[16:31], v[92:95], v[100:103], v[16:31]
	s_add_u32 m0, s101, 0xc000
	ds_read_b128 v[116:119], v131 offset:24576
	global_load_lds_dwordx4 v[58:59], off
	v_lshl_add_u64 v[58:59], v[58:59], 0, s[2:3]
	s_waitcnt lgkmcnt(2)
	v_mfma_f32_32x32x16_bf16 v[0:15], v[96:99], v[100:103], v[0:15]
	s_add_u32 m0, s101, 0xd000
	ds_read_b128 v[108:111], v121 offset:4096
	global_load_lds_dwordx4 v[60:61], off
	v_lshl_add_u64 v[60:61], v[60:61], 0, s[2:3]
	ds_read_b128 v[112:115], v121 offset:8192
	s_waitcnt lgkmcnt(2)
	v_mfma_f32_32x32x16_bf16 v[32:47], v[104:107], v[116:119], v[32:47]
	ds_read_b128 v[88:91], v122 offset:0
	s_waitcnt lgkmcnt(2)
	v_mfma_f32_32x32x16_bf16 v[16:31], v[108:111], v[116:119], v[16:31]
	ds_read_b128 v[100:103], v132 offset:24576
	s_waitcnt lgkmcnt(2)
	v_mfma_f32_32x32x16_bf16 v[0:15], v[112:115], v[116:119], v[0:15]
	ds_read_b128 v[92:95], v122 offset:4096
	ds_read_b128 v[96:99], v122 offset:8192
	s_waitcnt lgkmcnt(2)
	v_mfma_f32_32x32x16_bf16 v[32:47], v[88:91], v[100:103], v[32:47]
	ds_read_b128 v[104:107], v123 offset:0
	s_waitcnt lgkmcnt(2)
	v_mfma_f32_32x32x16_bf16 v[16:31], v[92:95], v[100:103], v[16:31]
	ds_read_b128 v[116:119], v133 offset:24576
	s_waitcnt lgkmcnt(2)
	v_mfma_f32_32x32x16_bf16 v[0:15], v[96:99], v[100:103], v[0:15]
	ds_read_b128 v[108:111], v123 offset:4096
	ds_read_b128 v[112:115], v123 offset:8192
	s_waitcnt vmcnt(0) lgkmcnt(0)
	s_barrier
	v_mfma_f32_32x32x16_bf16 v[32:47], v[104:107], v[116:119], v[32:47]
	s_add_u32 m0, s101, 0x0
	ds_read_b128 v[88:91], v120 offset:12288
	global_load_lds_dwordx4 v[48:49], off
	v_lshl_add_u64 v[48:49], v[48:49], 0, s[2:3]
	v_mfma_f32_32x32x16_bf16 v[16:31], v[108:111], v[116:119], v[16:31]
	s_add_u32 m0, s101, 0x1000
	ds_read_b128 v[100:103], v130 offset:40960
	global_load_lds_dwordx4 v[50:51], off
	v_lshl_add_u64 v[50:51], v[50:51], 0, s[2:3]
	v_mfma_f32_32x32x16_bf16 v[0:15], v[112:115], v[116:119], v[0:15]
	s_add_u32 m0, s101, 0x2000
	ds_read_b128 v[92:95], v120 offset:16384
	global_load_lds_dwordx4 v[52:53], off
	v_lshl_add_u64 v[52:53], v[52:53], 0, s[2:3]
	ds_read_b128 v[96:99], v120 offset:20480
	s_add_u32 m0, s101, 0x6000
	s_nop 0
	global_load_lds_dwordx4 v[54:55], off
	v_lshl_add_u64 v[54:55], v[54:55], 0, s[2:3]
	s_waitcnt lgkmcnt(2)
	v_mfma_f32_32x32x16_bf16 v[32:47], v[88:91], v[100:103], v[32:47]
	s_add_u32 m0, s101, 0x7000
	ds_read_b128 v[104:107], v121 offset:12288
	global_load_lds_dwordx4 v[56:57], off
	v_lshl_add_u64 v[56:57], v[56:57], 0, s[2:3]
	s_waitcnt lgkmcnt(2)
	v_mfma_f32_32x32x16_bf16 v[16:31], v[92:95], v[100:103], v[16:31]
	s_add_u32 m0, s101, 0x8000
	ds_read_b128 v[116:119], v131 offset:40960
	global_load_lds_dwordx4 v[58:59], off
	v_lshl_add_u64 v[58:59], v[58:59], 0, s[2:3]
	s_waitcnt lgkmcnt(2)
	v_mfma_f32_32x32x16_bf16 v[0:15], v[96:99], v[100:103], v[0:15]
	s_add_u32 m0, s101, 0x9000
	ds_read_b128 v[108:111], v121 offset:16384
	global_load_lds_dwordx4 v[60:61], off
	v_lshl_add_u64 v[60:61], v[60:61], 0, s[2:3]
	ds_read_b128 v[112:115], v121 offset:20480
	s_waitcnt lgkmcnt(2)
	v_mfma_f32_32x32x16_bf16 v[32:47], v[104:107], v[116:119], v[32:47]
	ds_read_b128 v[88:91], v122 offset:12288
	s_waitcnt lgkmcnt(2)
	v_mfma_f32_32x32x16_bf16 v[16:31], v[108:111], v[116:119], v[16:31]
	ds_read_b128 v[100:103], v132 offset:40960
	s_waitcnt lgkmcnt(2)
	v_mfma_f32_32x32x16_bf16 v[0:15], v[112:115], v[116:119], v[0:15]
	ds_read_b128 v[92:95], v122 offset:16384
	ds_read_b128 v[96:99], v122 offset:20480
	s_waitcnt lgkmcnt(2)
	v_mfma_f32_32x32x16_bf16 v[32:47], v[88:91], v[100:103], v[32:47]
	ds_read_b128 v[104:107], v123 offset:12288
	s_waitcnt lgkmcnt(2)
	v_mfma_f32_32x32x16_bf16 v[16:31], v[92:95], v[100:103], v[16:31]
	ds_read_b128 v[116:119], v133 offset:40960
	s_waitcnt lgkmcnt(2)
	v_mfma_f32_32x32x16_bf16 v[0:15], v[96:99], v[100:103], v[0:15]
	ds_read_b128 v[108:111], v123 offset:16384
	ds_read_b128 v[112:115], v123 offset:20480
	s_waitcnt vmcnt(0) lgkmcnt(0)
	s_barrier
	v_mfma_f32_32x32x16_bf16 v[32:47], v[104:107], v[116:119], v[32:47]
	s_add_u32 m0, s101, 0x3000
	ds_read_b128 v[88:91], v120 offset:0
	global_load_lds_dwordx4 v[48:49], off
	v_lshl_add_u64 v[48:49], v[48:49], 0, s[2:3]
	v_mfma_f32_32x32x16_bf16 v[16:31], v[108:111], v[116:119], v[16:31]
	s_add_u32 m0, s101, 0x4000
	ds_read_b128 v[100:103], v130 offset:24576
	global_load_lds_dwordx4 v[50:51], off
	v_lshl_add_u64 v[50:51], v[50:51], 0, s[2:3]
	v_mfma_f32_32x32x16_bf16 v[0:15], v[112:115], v[116:119], v[0:15]
	s_add_u32 m0, s101, 0x5000
	ds_read_b128 v[92:95], v120 offset:4096
	global_load_lds_dwordx4 v[52:53], off
	v_lshl_add_u64 v[52:53], v[52:53], 0, s[2:3]
	ds_read_b128 v[96:99], v120 offset:8192
	s_add_u32 m0, s101, 0xa000
	s_nop 0
	global_load_lds_dwordx4 v[54:55], off
	v_lshl_add_u64 v[54:55], v[54:55], 0, s[2:3]
	s_add_i32 s100, s100, -1
	s_cmp_lg_u32 s100, 0
	s_cbranch_scc1 .Lrsd_loop
	s_waitcnt lgkmcnt(2)
	v_mfma_f32_32x32x16_bf16 v[32:47], v[88:91], v[100:103], v[32:47]
	s_add_u32 m0, s101, 0xb000
	ds_read_b128 v[104:107], v121 offset:0
	global_load_lds_dwordx4 v[56:57], off
	v_lshl_add_u64 v[56:57], v[56:57], 0, s[2:3]
	s_waitcnt lgkmcnt(2)
	v_mfma_f32_32x32x16_bf16 v[16:31], v[92:95], v[100:103], v[16:31]
	s_add_u32 m0, s101, 0xc000
	ds_read_b128 v[116:119], v131 offset:24576
	global_load_lds_dwordx4 v[58:59], off
	v_lshl_add_u64 v[58:59], v[58:59], 0, s[2:3]
	s_waitcnt lgkmcnt(2)
	v_mfma_f32_32x32x16_bf16 v[0:15], v[96:99], v[100:103], v[0:15]
	s_add_u32 m0, s101, 0xd000
	ds_read_b128 v[108:111], v121 offset:4096
	global_load_lds_dwordx4 v[60:61], off
	v_lshl_add_u64 v[60:61], v[60:61], 0, s[2:3]
	ds_read_b128 v[112:115], v121 offset:8192
	s_waitcnt lgkmcnt(2)
	v_mfma_f32_32x32x16_bf16 v[32:47], v[104:107], v[116:119], v[32:47]
	ds_read_b128 v[88:91], v122 offset:0
	s_waitcnt lgkmcnt(2)
	v_mfma_f32_32x32x16_bf16 v[16:31], v[108:111], v[116:119], v[16:31]
	ds_read_b128 v[100:103], v132 offset:24576
	s_waitcnt lgkmcnt(2)
	v_mfma_f32_32x32x16_bf16 v[0:15], v[112:115], v[116:119], v[0:15]
	ds_read_b128 v[92:95], v122 offset:4096
	ds_read_b128 v[96:99], v122 offset:8192
	s_waitcnt lgkmcnt(2)
	v_mfma_f32_32x32x16_bf16 v[32:47], v[88:91], v[100:103], v[32:47]
	ds_read_b128 v[104:107], v123 offset:0
	s_waitcnt lgkmcnt(2)
	v_mfma_f32_32x32x16_bf16 v[16:31], v[92:95], v[100:103], v[16:31]
	ds_read_b128 v[116:119], v133 offset:24576
	s_waitcnt lgkmcnt(2)
	v_mfma_f32_32x32x16_bf16 v[0:15], v[96:99], v[100:103], v[0:15]
	ds_read_b128 v[108:111], v123 offset:4096
	ds_read_b128 v[112:115], v123 offset:8192
	s_waitcnt vmcnt(0) lgkmcnt(0)
	s_barrier
	v_mfma_f32_32x32x16_bf16 v[32:47], v[104:107], v[116:119], v[32:47]
	ds_read_b128 v[88:91], v120 offset:12288
	v_mfma_f32_32x32x16_bf16 v[16:31], v[108:111], v[116:119], v[16:31]
	ds_read_b128 v[100:103], v130 offset:40960
	v_mfma_f32_32x32x16_bf16 v[0:15], v[112:115], v[116:119], v[0:15]
	ds_read_b128 v[92:95], v120 offset:16384
	ds_read_b128 v[96:99], v120 offset:20480
	s_waitcnt lgkmcnt(2)
	v_mfma_f32_32x32x16_bf16 v[32:47], v[88:91], v[100:103], v[32:47]
	ds_read_b128 v[104:107], v121 offset:12288
	s_waitcnt lgkmcnt(2)
	v_mfma_f32_32x32x16_bf16 v[16:31], v[92:95], v[100:103], v[16:31]
	ds_read_b128 v[116:119], v131 offset:40960
	s_waitcnt lgkmcnt(2)
	v_mfma_f32_32x32x16_bf16 v[0:15], v[96:99], v[100:103], v[0:15]
	ds_read_b128 v[108:111], v121 offset:16384
	ds_read_b128 v[112:115], v121 offset:20480
	s_waitcnt lgkmcnt(2)
	v_mfma_f32_32x32x16_bf16 v[32:47], v[104:107], v[116:119], v[32:47]
	ds_read_b128 v[88:91], v122 offset:12288
	s_waitcnt lgkmcnt(2)
	v_mfma_f32_32x32x16_bf16 v[16:31], v[108:111], v[116:119], v[16:31]
	ds_read_b128 v[100:103], v132 offset:40960
	s_waitcnt lgkmcnt(2)
	v_mfma_f32_32x32x16_bf16 v[0:15], v[112:115], v[116:119], v[0:15]
	ds_read_b128 v[92:95], v122 offset:16384
	ds_read_b128 v[96:99], v122 offset:20480
	s_waitcnt lgkmcnt(2)
	v_mfma_f32_32x32x16_bf16 v[32:47], v[88:91], v[100:103], v[32:47]
	ds_read_b128 v[104:107], v123 offset:12288
	s_waitcnt lgkmcnt(2)
	v_mfma_f32_32x32x16_bf16 v[16:31], v[92:95], v[100:103], v[16:31]
	ds_read_b128 v[116:119], v133 offset:40960
	s_waitcnt lgkmcnt(2)
	v_mfma_f32_32x32x16_bf16 v[0:15], v[96:99], v[100:103], v[0:15]
	ds_read_b128 v[108:111], v123 offset:16384
	ds_read_b128 v[112:115], v123 offset:20480
	s_waitcnt vmcnt(0) lgkmcnt(0)
	s_barrier
	v_mfma_f32_32x32x16_bf16 v[32:47], v[104:107], v[116:119], v[32:47]
	v_mfma_f32_32x32x16_bf16 v[16:31], v[108:111], v[116:119], v[16:31]
	v_mfma_f32_32x32x16_bf16 v[0:15], v[112:115], v[116:119], v[0:15]
	s_nop 7
	s_nop 7
	s_branch .LBB0_1138

.LBB0_1336:
	s_ashr_i32 s14, s16, 31
	v_mov_b32_e32 v129, v127
	s_lshr_b32 s14, s14, 27
	s_add_i32 s14, s16, s14
	v_ashrrev_i32_e32 v20, 6, v129
	v_bfe_u32 v24, v129, 3, 3
	v_lshlrev_b32_e32 v25, 3, v20
	s_ashr_i32 s18, s14, 5
	s_and_b32 s14, s14, 0x3ffffe0
	v_or_b32_e32 v12, v25, v24
	s_sub_i32 s17, s16, s14
	v_lshrrev_b32_e32 v26, 1, v12
	s_mulk_i32 s17, 0xc0
	v_lshrrev_b32_e32 v0, 31, v129
	v_xor_b32_e32 v2, v26, v129
	v_add_u32_e32 v21, v20, v0
	v_and_b32_e32 v23, 63, v129
	v_add_u32_e32 v0, s17, v12
	v_lshlrev_b32_e32 v2, 4, v2
	v_add_u32_e32 v14, 32, v12
	v_ashrrev_i32_e32 v1, 31, v0
	v_and_b32_e32 v124, 0x70, v2
	v_add_u32_e32 v2, s17, v14
	v_add_u32_e32 v16, 64, v12
	s_add_i32 s15, s17, 0x80
	v_lshlrev_b32_e32 v23, 4, v23
	v_lshlrev_b64 v[0:1], 11, v[0:1]
	v_ashrrev_i32_e32 v3, 31, v2
	v_add_u32_e32 v4, s17, v16
	v_add_u32_e32 v18, 0x60, v12
	v_add_u32_e32 v8, s15, v12
	s_add_i32 s15, s17, 0xa0
	v_lshl_or_b32 v142, v20, 10, v23
	v_lshl_add_u64 v[0:1], s[6:7], 0, v[0:1]
	v_lshlrev_b64 v[2:3], 11, v[2:3]
	v_ashrrev_i32_e32 v5, 31, v4
	v_add_u32_e32 v6, s17, v18
	v_add_u32_e32 v10, s15, v12
	v_readfirstlane_b32 s15, v142
	v_add_u32_e32 v144, 0x1000, v142
	v_lshl_add_u64 v[0:1], v[0:1], 0, v[124:125]
	v_lshl_add_u64 v[2:3], s[6:7], 0, v[2:3]
	v_lshlrev_b64 v[4:5], 11, v[4:5]
	v_ashrrev_i32_e32 v7, 31, v6
	s_mov_b32 m0, s15
	v_readfirstlane_b32 s15, v144
	v_add_u32_e32 v145, 0x2000, v142
	s_lshl_b32 s14, s18, 7
	v_lshl_add_u64 v[2:3], v[2:3], 0, v[124:125]
	v_lshl_add_u64 v[4:5], s[6:7], 0, v[4:5]
	v_lshlrev_b64 v[6:7], 11, v[6:7]
	v_ashrrev_i32_e32 v9, 31, v8
	global_load_lds_dwordx4 v[0:1], off
	s_mov_b32 m0, s15
	v_readfirstlane_b32 s15, v145
	v_add_u32_e32 v146, 0x3000, v142
	v_lshl_add_u64 v[4:5], v[4:5], 0, v[124:125]
	v_lshl_add_u64 v[6:7], s[6:7], 0, v[6:7]
	v_lshlrev_b64 v[8:9], 11, v[8:9]
	v_ashrrev_i32_e32 v11, 31, v10
	v_add_u32_e32 v12, s14, v12
	global_load_lds_dwordx4 v[2:3], off
	s_mov_b32 m0, s15
	v_readfirstlane_b32 s15, v146
	v_add_u32_e32 v147, 0x4000, v142
	v_lshl_add_u64 v[6:7], v[6:7], 0, v[124:125]
	v_lshl_add_u64 v[8:9], s[6:7], 0, v[8:9]
	v_lshlrev_b64 v[10:11], 11, v[10:11]
	v_ashrrev_i32_e32 v13, 31, v12
	v_add_u32_e32 v14, s14, v14
	global_load_lds_dwordx4 v[4:5], off
	s_mov_b32 m0, s15
	v_readfirstlane_b32 s15, v147
	v_add_u32_e32 v148, 0x5000, v142
	v_lshl_add_u64 v[8:9], v[8:9], 0, v[124:125]
	v_lshl_add_u64 v[10:11], s[6:7], 0, v[10:11]
	v_lshlrev_b64 v[12:13], 11, v[12:13]
	v_ashrrev_i32_e32 v15, 31, v14
	v_add_u32_e32 v16, s14, v16
	v_add_u32_e32 v143, 0xc000, v142
	global_load_lds_dwordx4 v[6:7], off
	s_mov_b32 m0, s15
	v_readfirstlane_b32 s15, v148
	v_lshl_add_u64 v[10:11], v[10:11], 0, v[124:125]
	v_lshl_add_u64 v[12:13], s[10:11], 0, v[12:13]
	v_lshlrev_b64 v[14:15], 11, v[14:15]
	v_ashrrev_i32_e32 v17, 31, v16
	v_add_u32_e32 v18, s14, v18
	global_load_lds_dwordx4 v[8:9], off
	s_mov_b32 m0, s15
	v_readfirstlane_b32 s15, v143
	v_add_u32_e32 v150, 0xd000, v142
	v_lshl_add_u64 v[12:13], v[12:13], 0, v[124:125]
	v_lshl_add_u64 v[14:15], s[10:11], 0, v[14:15]
	v_lshlrev_b64 v[16:17], 11, v[16:17]
	v_ashrrev_i32_e32 v19, 31, v18
	global_load_lds_dwordx4 v[10:11], off
	s_mov_b32 m0, s15
	v_readfirstlane_b32 s15, v150
	v_add_u32_e32 v153, 0xe000, v142
	v_lshl_add_u64 v[14:15], v[14:15], 0, v[124:125]
	v_lshl_add_u64 v[16:17], s[10:11], 0, v[16:17]
	v_lshlrev_b64 v[18:19], 11, v[18:19]
	global_load_lds_dwordx4 v[12:13], off
	s_mov_b32 m0, s15
	v_readfirstlane_b32 s15, v153
	v_add_u32_e32 v154, 0xf000, v142
	v_lshl_add_u64 v[16:17], v[16:17], 0, v[124:125]
	v_lshl_add_u64 v[18:19], s[10:11], 0, v[18:19]
	global_load_lds_dwordx4 v[14:15], off
	s_mov_b32 m0, s15
	v_readfirstlane_b32 s15, v154
	v_lshl_add_u64 v[18:19], v[18:19], 0, v[124:125]
	global_load_lds_dwordx4 v[16:17], off
	s_mov_b32 m0, s15
	v_lshrrev_b32_e32 v22, 1, v21
	global_load_lds_dwordx4 v[18:19], off
	v_and_b32_e32 v149, 31, v129
	v_mul_lo_u32 v152, v22, s80
	v_and_b32_e32 v0, -2, v21
	v_or_b32_e32 v1, v152, v149
	v_sub_u32_e32 v151, v20, v0
	v_lshlrev_b32_e32 v155, 7, v1
	v_lshlrev_b32_e32 v1, 7, v149
	v_lshrrev_b32_e32 v23, 1, v129
	v_lshl_or_b32 v182, v151, 13, v1
	v_bfe_u32 v1, v129, 5, 1
	v_bfe_u32 v0, v129, 1, 3
	v_bitop3_b32 v2, v1, v23, 7 bitop3:0x78
	v_lshlrev_b32_e32 v184, 4, v2
	v_bitop3_b32 v2, v1, v0, 2 bitop3:0x36
	v_lshlrev_b32_e32 v185, 4, v2
	v_bitop3_b32 v2, v1, v0, 4 bitop3:0x36
	v_bitop3_b32 v0, v1, v0, 6 bitop3:0x36
	v_lshlrev_b32_e32 v187, 4, v0
	v_bitop3_b32 v0, v26, 7, v129 bitop3:0x48
	s_mul_i32 s15, s16, 0xc0
	v_lshlrev_b32_e32 v124, 4, v0
	v_or_b32_e32 v0, s15, v24
	v_add_u32_e32 v0, v0, v25
	s_mul_i32 s19, s18, 0x1800
	v_subrev_u32_e32 v0, s19, v0
	v_ashrrev_i32_e32 v1, 31, v0
	v_or_b32_e32 v4, 32, v24
	v_lshlrev_b32_e32 v186, 4, v2
	v_lshlrev_b64 v[2:3], 11, v[0:1]
	v_or_b32_e32 v1, s15, v4
	v_add_u32_e32 v1, v1, v25
	v_lshl_add_u64 v[96:97], s[6:7], 0, v[2:3]
	v_subrev_u32_e32 v2, s19, v1
	v_ashrrev_i32_e32 v3, 31, v2
	v_or_b32_e32 v5, 64, v24
	v_lshlrev_b64 v[2:3], 11, v[2:3]
	v_add3_u32 v1, v5, s15, v25
	v_lshl_add_u64 v[98:99], s[6:7], 0, v[2:3]
	v_subrev_u32_e32 v2, s19, v1
	v_ashrrev_i32_e32 v3, 31, v2
	v_or_b32_e32 v6, 0x60, v24
	v_lshlrev_b64 v[2:3], 11, v[2:3]
	v_add3_u32 v1, v6, s15, v25
	v_lshl_add_u64 v[100:101], s[6:7], 0, v[2:3]
	v_subrev_u32_e32 v2, s19, v1
	v_ashrrev_i32_e32 v3, 31, v2
	v_lshlrev_b64 v[2:3], 11, v[2:3]
	v_lshl_add_u64 v[102:103], s[6:7], 0, v[2:3]
	v_add_u32_e32 v2, 0x80, v0
	v_add_u32_e32 v0, 0xa0, v0
	v_ashrrev_i32_e32 v1, 31, v0
	v_lshlrev_b64 v[0:1], 11, v[0:1]
	v_lshl_add_u64 v[106:107], s[6:7], 0, v[0:1]
	v_or_b32_e32 v0, s14, v24
	v_add_u32_e32 v0, v0, v25
	v_ashrrev_i32_e32 v1, 31, v0
	v_lshlrev_b64 v[0:1], 11, v[0:1]
	v_lshl_add_u64 v[108:109], s[12:13], 0, v[0:1]
	v_or_b32_e32 v0, s14, v4
	v_add_u32_e32 v0, v0, v25
	v_ashrrev_i32_e32 v1, 31, v0
	v_lshlrev_b64 v[0:1], 11, v[0:1]
	v_lshl_add_u64 v[110:111], s[12:13], 0, v[0:1]
	v_or_b32_e32 v0, s14, v5
	v_add_u32_e32 v0, v0, v25
	v_ashrrev_i32_e32 v1, 31, v0
	v_lshlrev_b64 v[0:1], 11, v[0:1]
	v_lshl_add_u64 v[112:113], s[12:13], 0, v[0:1]
	v_or_b32_e32 v0, s14, v6
	v_add_u32_e32 v0, v0, v25
	s_waitcnt vmcnt(0)
	v_ashrrev_i32_e32 v3, 31, v2
	v_ashrrev_i32_e32 v1, 31, v0
	v_lshlrev_b64 v[2:3], 11, v[2:3]
	v_lshlrev_b64 v[0:1], 11, v[0:1]
	v_mov_b32_e32 v64, 0
	v_add_u32_e32 v183, 0x10000, v182
	v_lshl_add_u64 v[104:105], s[6:7], 0, v[2:3]
	v_lshl_add_u64 v[114:115], s[12:13], 0, v[0:1]
	s_mov_b32 s19, 0
	v_mov_b32_e32 v65, v64
	v_mov_b32_e32 v66, v64
	v_mov_b32_e32 v67, v64
	v_mov_b32_e32 v68, v64
	v_mov_b32_e32 v69, v64
	v_mov_b32_e32 v70, v64
	v_mov_b32_e32 v71, v64
	v_mov_b32_e32 v72, v64
	v_mov_b32_e32 v73, v64
	v_mov_b32_e32 v74, v64
	v_mov_b32_e32 v75, v64
	v_mov_b32_e32 v76, v64
	v_mov_b32_e32 v77, v64
	v_mov_b32_e32 v78, v64
	v_mov_b32_e32 v79, v64
	v_mov_b32_e32 v80, v64
	v_mov_b32_e32 v81, v64
	v_mov_b32_e32 v82, v64
	v_mov_b32_e32 v83, v64
	v_mov_b32_e32 v84, v64
	v_mov_b32_e32 v85, v64
	v_mov_b32_e32 v86, v64
	v_mov_b32_e32 v87, v64
	v_mov_b32_e32 v88, v64
	v_mov_b32_e32 v89, v64
	v_mov_b32_e32 v90, v64
	v_mov_b32_e32 v91, v64
	v_mov_b32_e32 v92, v64
	v_mov_b32_e32 v93, v64
	v_mov_b32_e32 v94, v64
	v_mov_b32_e32 v95, v64
	v_mov_b32_e32 v32, v64
	v_mov_b32_e32 v33, v64
	v_mov_b32_e32 v34, v64
	v_mov_b32_e32 v35, v64
	v_mov_b32_e32 v36, v64
	v_mov_b32_e32 v37, v64
	v_mov_b32_e32 v38, v64
	v_mov_b32_e32 v39, v64
	v_mov_b32_e32 v40, v64
	v_mov_b32_e32 v41, v64
	v_mov_b32_e32 v42, v64
	v_mov_b32_e32 v43, v64
	v_mov_b32_e32 v44, v64
	v_mov_b32_e32 v45, v64
	v_mov_b32_e32 v46, v64
	v_mov_b32_e32 v47, v64
	v_mov_b32_e32 v48, v64
	v_mov_b32_e32 v49, v64
	v_mov_b32_e32 v50, v64
	v_mov_b32_e32 v51, v64
	v_mov_b32_e32 v52, v64
	v_mov_b32_e32 v53, v64
	v_mov_b32_e32 v54, v64
	v_mov_b32_e32 v55, v64
	v_mov_b32_e32 v56, v64
	v_mov_b32_e32 v57, v64
	v_mov_b32_e32 v58, v64
	v_mov_b32_e32 v59, v64
	v_mov_b32_e32 v60, v64
	v_mov_b32_e32 v61, v64
	v_mov_b32_e32 v62, v64
	v_mov_b32_e32 v63, v64
	v_mov_b32_e32 v0, v64
	v_mov_b32_e32 v1, v64
	v_mov_b32_e32 v2, v64
	v_mov_b32_e32 v3, v64
	v_mov_b32_e32 v4, v64
	v_mov_b32_e32 v5, v64
	v_mov_b32_e32 v6, v64
	v_mov_b32_e32 v7, v64
	v_mov_b32_e32 v8, v64
	v_mov_b32_e32 v9, v64
	v_mov_b32_e32 v10, v64
	v_mov_b32_e32 v11, v64
	v_mov_b32_e32 v12, v64
	v_mov_b32_e32 v13, v64
	v_mov_b32_e32 v14, v64
	v_mov_b32_e32 v15, v64
	v_mov_b32_e32 v16, v64
	v_mov_b32_e32 v17, v64
	v_mov_b32_e32 v18, v64
	v_mov_b32_e32 v19, v64
	v_mov_b32_e32 v20, v64
	v_mov_b32_e32 v21, v64
	v_mov_b32_e32 v22, v64
	v_mov_b32_e32 v23, v64
	v_mov_b32_e32 v24, v64
	v_mov_b32_e32 v25, v64
	v_mov_b32_e32 v26, v64
	v_mov_b32_e32 v27, v64
	v_mov_b32_e32 v28, v64
	v_mov_b32_e32 v29, v64
	v_mov_b32_e32 v30, v64
	v_mov_b32_e32 v31, v64
	s_waitcnt vmcnt(0) lgkmcnt(0)
	s_barrier
	v_readfirstlane_b32 s101, v142
	s_sub_u32 vcc_lo, s10, s12
	s_subb_u32 vcc_hi, s11, s13
	v_mov_b32_e32 v130, v124
	v_mov_b32_e32 v131, 0
	v_lshl_add_u64 v[108:109], v[108:109], 0, vcc
	v_lshl_add_u64 v[110:111], v[110:111], 0, vcc
	v_lshl_add_u64 v[112:113], v[112:113], 0, vcc
	v_lshl_add_u64 v[114:115], v[114:115], 0, vcc
	v_lshl_add_u64 v[96:97], v[96:97], 0, v[130:131]
	v_lshl_add_u64 v[98:99], v[98:99], 0, v[130:131]
	v_lshl_add_u64 v[100:101], v[100:101], 0, v[130:131]
	v_lshl_add_u64 v[102:103], v[102:103], 0, v[130:131]
	v_lshl_add_u64 v[104:105], v[104:105], 0, v[130:131]
	v_lshl_add_u64 v[106:107], v[106:107], 0, v[130:131]
	v_lshl_add_u64 v[108:109], v[108:109], 0, v[130:131]
	v_lshl_add_u64 v[110:111], v[110:111], 0, v[130:131]
	v_lshl_add_u64 v[112:113], v[112:113], 0, v[130:131]
	v_lshl_add_u64 v[114:115], v[114:115], 0, v[130:131]
	v_add_u32_e32 v116, v155, v184
	v_add_u32_e32 v117, v155, v185
	v_add_u32_e32 v118, v155, v186
	v_add_u32_e32 v119, v155, v187
	v_add_u32_e32 v120, v182, v184
	v_add_u32_e32 v121, v182, v185
	v_add_u32_e32 v122, v182, v186
	v_add_u32_e32 v123, v182, v187
	v_add_u32_e32 v120, 0x8000, v120
	v_add_u32_e32 v121, 0x8000, v121
	v_add_u32_e32 v122, 0x8000, v122
	v_add_u32_e32 v123, 0x8000, v123
	v_lshl_add_u64 v[96:97], v[96:97], 0, s[2:3]
	v_lshl_add_u64 v[98:99], v[98:99], 0, s[2:3]
	v_lshl_add_u64 v[100:101], v[100:101], 0, s[2:3]
	v_lshl_add_u64 v[102:103], v[102:103], 0, s[2:3]
	v_lshl_add_u64 v[104:105], v[104:105], 0, s[2:3]
	v_lshl_add_u64 v[106:107], v[106:107], 0, s[2:3]
	v_lshl_add_u64 v[108:109], v[108:109], 0, s[2:3]
	v_lshl_add_u64 v[110:111], v[110:111], 0, s[2:3]
	v_lshl_add_u64 v[112:113], v[112:113], 0, s[2:3]
	v_lshl_add_u64 v[114:115], v[114:115], 0, s[2:3]
	ds_read_b128 v[192:195], v116 offset:0
	ds_read_b128 v[204:207], v120 offset:16384
	ds_read_b128 v[208:211], v120 offset:20480
	ds_read_b128 v[196:199], v116 offset:4096
	ds_read_b128 v[200:203], v116 offset:8192
	s_add_u32 m0, s101, 0x6000
	s_nop 0
	global_load_lds_dwordx4 v[96:97], off
	v_lshl_add_u64 v[96:97], v[96:97], 0, s[2:3]
	s_add_u32 m0, s101, 0x7000
	s_nop 0
	global_load_lds_dwordx4 v[98:99], off
	v_lshl_add_u64 v[98:99], v[98:99], 0, s[2:3]
	s_add_u32 m0, s101, 0x8000
	s_nop 0
	global_load_lds_dwordx4 v[100:101], off
	v_lshl_add_u64 v[100:101], v[100:101], 0, s[2:3]
	s_add_u32 m0, s101, 0x9000
	s_nop 0
	global_load_lds_dwordx4 v[102:103], off
	v_lshl_add_u64 v[102:103], v[102:103], 0, s[2:3]
	s_add_u32 m0, s101, 0xa000
	s_nop 0
	global_load_lds_dwordx4 v[104:105], off
	v_lshl_add_u64 v[104:105], v[104:105], 0, s[2:3]
	s_add_u32 m0, s101, 0xb000
	s_nop 0
	global_load_lds_dwordx4 v[106:107], off
	v_lshl_add_u64 v[106:107], v[106:107], 0, s[2:3]
	s_mov_b32 s100, 7

	.amdhsa_kernel _Z4mega6Params
		.amdhsa_group_segment_fixed_size 81920
		.amdhsa_private_segment_fixed_size 0
		.amdhsa_kernarg_size 528
		.amdhsa_user_sgpr_count 2
		.amdhsa_user_sgpr_dispatch_ptr 0
		.amdhsa_user_sgpr_queue_ptr 0
		.amdhsa_user_sgpr_kernarg_segment_ptr 1
		.amdhsa_user_sgpr_dispatch_id 0
		.amdhsa_user_sgpr_kernarg_preload_length 0
		.amdhsa_user_sgpr_kernarg_preload_offset 0
		.amdhsa_user_sgpr_private_segment_size 0
		.amdhsa_uses_dynamic_stack 0
		.amdhsa_enable_private_segment 0
		.amdhsa_system_sgpr_workgroup_id_x 1
		.amdhsa_system_sgpr_workgroup_id_y 0
		.amdhsa_system_sgpr_workgroup_id_z 0
		.amdhsa_system_sgpr_workgroup_info 0
		.amdhsa_system_vgpr_workitem_id 2
		.amdhsa_next_free_vgpr 243
		.amdhsa_next_free_sgpr 102
		.amdhsa_accum_offset 244
		.amdhsa_reserve_vcc 1
		.amdhsa_float_round_mode_32 0
		.amdhsa_float_round_mode_16_64 0
		.amdhsa_float_denorm_mode_32 3
		.amdhsa_float_denorm_mode_16_64 3
		.amdhsa_dx10_clamp 1
		.amdhsa_ieee_mode 1
		.amdhsa_fp16_overflow 0
		.amdhsa_tg_split 0
		.amdhsa_exception_fp_ieee_invalid_op 0
		.amdhsa_exception_fp_denorm_src 0
		.amdhsa_exception_fp_ieee_div_zero 0
		.amdhsa_exception_fp_ieee_overflow 0
		.amdhsa_exception_fp_ieee_underflow 0
		.amdhsa_exception_fp_ieee_inexact 0
		.amdhsa_exception_int_div_zero 0
	.end_amdhsa_kernel

amdhsa.kernels:
  - .agpr_count:     0
    .args:
      - .offset:         0
        .size:           272
        .value_kind:     by_value
      - .offset:         272
        .size:           4
        .value_kind:     hidden_block_count_x
      - .offset:         276
        .size:           4
        .value_kind:     hidden_block_count_y
      - .offset:         280
        .size:           4
        .value_kind:     hidden_block_count_z
      - .offset:         284
        .size:           2
        .value_kind:     hidden_group_size_x
      - .offset:         286
        .size:           2
        .value_kind:     hidden_group_size_y
      - .offset:         288
        .size:           2
        .value_kind:     hidden_group_size_z
      - .offset:         290
        .size:           2
        .value_kind:     hidden_remainder_x
      - .offset:         292
        .size:           2
        .value_kind:     hidden_remainder_y
      - .offset:         294
        .size:           2
        .value_kind:     hidden_remainder_z
      - .offset:         312
        .size:           8
        .value_kind:     hidden_global_offset_x
      - .offset:         320
        .size:           8
        .value_kind:     hidden_global_offset_y
      - .offset:         328
        .size:           8
        .value_kind:     hidden_global_offset_z
      - .offset:         336
        .size:           2
        .value_kind:     hidden_grid_dims
      - .offset:         360
        .size:           8
        .value_kind:     hidden_multigrid_sync_arg
    .group_segment_fixed_size: 81920
    .kernarg_segment_align: 8
    .kernarg_segment_size: 528
    .language:       OpenCL C
    .language_version:
      - 2
      - 0
    .max_flat_workgroup_size: 256
    .name:           _Z4mega6Params
    .private_segment_fixed_size: 0
    .sgpr_count:     108
    .sgpr_spill_count: 303
    .symbol:         _Z4mega6Params.kd
    .uniform_work_group_size: 1
    .uses_dynamic_stack: false
    .vgpr_count:     243
    .vgpr_spill_count: 0
    .wavefront_size: 64
